# previous best combination + rw_scan per-row v values staged transposed and read four steps at a time (one LDS read fewer in three of four steps)
# speedup vs baseline: 1.0104x; 1.0104x over previous
.LBB0_768:
	s_lshl_b32 s0, s8, 5
	s_and_b32 s0, s0, 0xe0
	s_ashr_i32 s11, s8, 3
	s_add_i32 s0, s0, s11
	s_bfe_u32 s9, s0, 0x40003
	s_lshl_b32 s6, s9, 8
	v_lshl_add_u64 v[0:1], v[52:53], 0, s[6:7]
	v_lshl_add_u64 v[4:5], v[54:55], 0, s[6:7]
	global_load_dwordx4 v[0:3], v[0:1], off
	s_bfe_u32 s6, s11, 0x10002
	global_load_dwordx4 v[4:7], v[4:5], off
	s_ashr_i32 s12, s0, 7
	s_cmp_eq_u32 s6, 0
	s_cselect_b64 s[46:47], -1, 0
	s_and_saveexec_b64 s[0:1], s[36:37]
	s_xor_b64 s[0:1], exec, s[0:1]
	v_cndmask_b32_e64 v8, v59, v51, s[46:47]
	s_lshl_b32 s10, s12, 13
	s_lshl_b32 s13, s12, 8
	v_add_u32_e32 v8, s10, v8
	v_mov_b32_e32 v10, s13
	v_mov_b32_e32 v98, s10
	s_or_saveexec_b64 s[0:1], s[0:1]
	s_lshl_b32 s10, s9, 6
	s_xor_b64 exec, exec, s[0:1]
	v_cndmask_b32_e64 v8, v71, v49, s[46:47]
	s_lshl_b32 s13, s12, 8
	v_add_u32_e32 v8, s13, v8
	s_lshl_b32 s12, s12, 13
	v_add_u32_e32 v8, 0x4000, v8
	v_mov_b32_e32 v10, s13
	v_mov_b32_e32 v98, s12
	s_or_b64 exec, exec, s[0:1]
	v_mov_b32_e32 v131, v8
	s_lshl_b32 s0, s6, 5
	s_sub_i32 s0, 16, s0
	v_mov_b32_e32 v132, s0
	v_sub_u32_e32 v133, 0x1fff, v49
	v_cndmask_b32_e64 v133, v133, v49, s[46:47]
	v_add_u32_e32 v133, v98, v133
	s_lshl_b32 s0, s9, 2
	v_mov_b32_e32 v134, s0
	v_lshlrev_b32_e32 v130, 6, v48
	v_lshl_add_u32 v130, v49, 2, v130
	v_add_u32_e32 v130, 0xe810, v130
	s_mul_i32 s6, s6, 0x2100000
	v_ashrrev_i32_e32 v9, 31, v8
	s_add_u32 s24, s86, s6
	v_or_b32_e32 v58, s10, v50
	v_lshlrev_b64 v[12:13], 11, v[8:9]
	s_addc_u32 s25, s87, 0
	v_readlane_b32 s0, v182, 23
	v_lshl_or_b32 v14, v58, 1, v12
	v_mov_b32_e32 v15, v13
	v_readlane_b32 s1, v182, 24
	s_add_u32 s20, s0, s6
	v_lshl_add_u64 v[16:17], s[2:3], 0, v[14:15]
	v_lshl_or_b32 v8, v8, 4, s9
	s_addc_u32 s21, s1, 0
	global_load_dwordx2 v[16:17], v[16:17], off
	v_ashrrev_i32_e32 v9, 31, v8
	v_lshl_add_u64 v[18:19], s[90:91], 0, v[14:15]
	v_lshl_add_u64 v[20:21], s[20:21], 0, v[14:15]
	v_lshl_add_u64 v[14:15], s[24:25], 0, v[14:15]
	v_lshl_add_u64 v[8:9], v[8:9], 2, s[74:75]
	global_load_dwordx2 v[18:19], v[18:19], off
	s_add_u32 vcc_lo, s22, s6
	global_load_dwordx2 v[22:23], v[14:15], off
	v_readlane_b32 s12, v181, 42
	global_load_dword v8, v[8:9], off
	s_addc_u32 vcc_hi, s23, 0
	global_load_dwordx2 v[20:21], v[20:21], off
	s_lshl_b32 s0, s11, 4
	v_readlane_b32 s13, v181, 43
	s_and_b32 s11, s0, 48
	s_lshl_b32 s6, s10, 1
	v_lshl_add_u64 v[12:13], s[12:13], 0, v[12:13]
	v_lshl_add_u64 v[12:13], v[12:13], 0, s[6:7]
	s_lshl_b32 s0, s11, 1
	s_mov_b32 s1, s7
	v_lshl_add_u64 v[12:13], v[12:13], 0, s[0:1]
	v_lshl_add_u64 v[24:25], v[12:13], 0, v[68:69]
	s_add_i32 s10, s10, s11
	s_add_u32 s1, s12, s6
	s_addc_u32 s6, s13, 0
	s_add_u32 s0, s1, s0
	s_addc_u32 s1, s6, 0
	v_lshl_add_u64 v[60:61], s[0:1], 0, v[68:69]
	v_add_u32_e32 v99, 0x4000, v10
	s_mov_b32 s6, 0
	v_mov_b32_e32 v100, v97
	v_mov_b32_e32 v101, v96
	s_waitcnt vmcnt(4)
	v_lshlrev_b32_e32 v26, 16, v16
	v_and_b32_e32 v27, 0xffff0000, v16
	v_pk_mul_f32 v[12:13], v[0:1], v[26:27]
	s_waitcnt vmcnt(2)
	v_alignbit_b32 v11, v23, v22, 16
	s_waitcnt vmcnt(1)
	v_pk_mul_f32 v[30:31], v[12:13], v[8:9] op_sel_hi:[1,0]
	v_alignbit_b32 v9, v17, v16, 16
	v_and_b32_e32 v17, 0xffff0000, v17
	v_and_b32_e32 v16, 0xffff0000, v9
	v_pk_mul_f32 v[14:15], v[2:3], v[16:17]
	v_xor_b32_e32 v13, 0x80000000, v31
	v_pk_mul_f32 v[8:9], v[8:9], v[14:15] op_sel_hi:[0,1]
	v_xor_b32_e32 v12, 0x80000000, v30
	v_xor_b32_e32 v15, 0x80000000, v9
	v_xor_b32_e32 v14, 0x80000000, v8
	ds_write_b128 v81, v[12:15]
	v_lshlrev_b32_e32 v12, 16, v22
	v_and_b32_e32 v13, 0xffff0000, v22
	v_and_b32_e32 v15, 0xffff0000, v23
	v_and_b32_e32 v14, 0xffff0000, v11
	s_waitcnt vmcnt(0)
	v_alignbit_b32 v11, v21, v20, 16
	v_lshlrev_b32_e32 v28, 16, v20
	v_and_b32_e32 v29, 0xffff0000, v20
	v_pk_add_f32 v[12:13], v[12:13], 1.0 op_sel_hi:[1,0] neg_lo:[1,0] neg_hi:[1,0]
	v_pk_add_f32 v[14:15], v[14:15], 1.0 op_sel_hi:[1,0] neg_lo:[1,0] neg_hi:[1,0]
	v_and_b32_e32 v21, 0xffff0000, v21
	v_and_b32_e32 v20, 0xffff0000, v11
	ds_write_b128 v81, v[12:15] offset:256
	v_pk_mul_f32 v[14:15], v[8:9], v[20:21]
	v_pk_add_f32 v[8:9], v[28:29], -1.0 op_sel_hi:[1,0]
	v_pk_mul_f32 v[12:13], v[30:31], v[28:29]
	v_pk_fma_f32 v[8:9], v[4:5], v[8:9], 1.0 op_sel_hi:[1,1,0]
	ds_write_b128 v81, v[12:15] offset:512
	v_pk_mul_f32 v[12:13], v[8:9], v[26:27]
	v_pk_add_f32 v[8:9], v[20:21], -1.0 op_sel_hi:[1,0]
	s_nop 0
	v_pk_fma_f32 v[8:9], v[6:7], v[8:9], 1.0 op_sel_hi:[1,1,0]
	s_nop 0
	v_pk_mul_f32 v[14:15], v[8:9], v[16:17]
	v_alignbit_b32 v8, v19, v18, 16
	ds_write_b128 v81, v[12:15] offset:768
	v_and_b32_e32 v14, 0xffff0000, v8
	global_load_ushort v8, v[24:25], off
	v_and_b32_e32 v15, 0xffff0000, v19
	v_lshlrev_b32_e32 v12, 16, v18
	v_and_b32_e32 v13, 0xffff0000, v18
	ds_write_b128 v81, v[12:15] offset:1024
	s_waitcnt vmcnt(0)
	v_lshlrev_b32_e32 v8, 16, v8
	ds_write_b32 v88, v8 offset:1280
	ds_write_b32 v130, v8
	v_add_u32_e32 v8, s10, v89
	v_ashrrev_i32_e32 v9, 31, v8
	v_lshl_add_u64 v[56:57], v[8:9], 1, vcc
	v_mov_b32_e32 v8, 0
	s_mov_b32 s10, 0
	v_mov_b32_e32 v9, v8
	v_mov_b32_e32 v10, v8
	v_mov_b32_e32 v11, v8
	v_lshlrev_b32_e32 v58, 1, v58
	v_readlane_b32 s100, v181, 42
	v_readlane_b32 s101, v181, 43
	v_sub_u32_e32 v12, 0xff, v48
	v_cndmask_b32_e64 v12, v12, v48, s[46:47]
	v_add_u32_e32 v100, v99, v12
	v_sub_u32_e32 v12, 0x1fff, v48
	v_cndmask_b32_e64 v12, v12, v48, s[46:47]
	v_add_u32_e32 v101, v98, v12
	v_subrev_u32_e32 v60, s100, v60
	v_subrev_u32_e32 v99, s100, v56
	v_add_u32_e32 v131, v132, v131
	v_lshl_add_u32 v13, v131, 11, v58
	v_lshl_add_u32 v14, v131, 6, v134
	v_lshl_add_u32 v15, v131, 11, v60
	global_load_dwordx2 v[74:75], v13, s[2:3]
	global_load_dwordx2 v[62:63], v13, s[90:91]
	global_load_dwordx2 v[76:77], v13, s[24:25]
	global_load_dword v78, v14, s[74:75]
	global_load_dwordx2 v[72:73], v13, s[20:21]
	global_load_ushort v102, v15, s[100:101]
	s_waitcnt lgkmcnt(0)
	s_barrier
	s_branch .LBB0_774
.LBB0_774:
	s_and_b32 s11, s10, 1
	s_mul_i32 s0, s11, 0x5400
	s_add_i32 s0, s0, 16
	v_lshl_add_u32 v126, v87, 2, s0
	v_add3_u32 v124, s0, v91, v92
	s_lshl_b32 s0, s11, 10
	s_add_i32 s0, s0, 0xe810
	v_add_u32_e32 v127, v91, v92
	v_lshl_add_u32 v127, v127, 4, s0
	ds_read_b128 v[136:139], v127 offset:0
	ds_read_b128 v[184:187], v126 offset:0
	ds_read_b128 v[196:199], v126 offset:768
	ds_read_b128 v[188:191], v126 offset:256
	ds_read_b128 v[200:203], v126 offset:1024
	ds_read_b128 v[192:195], v126 offset:512
	ds_read_b128 v[206:209], v126 offset:1344
	ds_read_b128 v[218:221], v126 offset:2112
	ds_read_b128 v[210:213], v126 offset:1600
	ds_read_b128 v[222:225], v126 offset:2368
	ds_read_b128 v[214:217], v126 offset:1856
	s_waitcnt lgkmcnt(5)
	v_pk_mul_f32 v[250:251], v[8:9], v[184:185]
	v_pk_mul_f32 v[252:253], v[136:137], v[196:197] op_sel_hi:[0,1]
	v_pk_fma_f32 v[250:251], v[10:11], v[186:187], v[250:251]
	v_pk_mul_f32 v[254:255], v[136:137], v[198:199] op_sel_hi:[0,1]
	v_add_f32_e32 v14, v250, v251
	v_pk_fma_f32 v[252:253], v[8:9], v[188:189], v[252:253]
	v_pk_fma_f32 v[254:255], v[10:11], v[190:191], v[254:255]
	v_add_f32_dpp v14, v14, v14 quad_perm:[1,0,3,2] row_mask:0xf bank_mask:0xf bound_ctrl:1
	ds_read_b128 v[228:231], v126 offset:2688
	ds_read_b128 v[240:243], v126 offset:3456
	v_add_f32_dpp v14, v14, v14 quad_perm:[2,3,0,1] row_mask:0xf bank_mask:0xf bound_ctrl:1
	ds_read_b128 v[232:235], v126 offset:2944
	ds_read_b128 v[244:247], v126 offset:3712
	v_add_f32_dpp v14, v14, v14 row_half_mirror row_mask:0xf bank_mask:0xf bound_ctrl:1
	ds_read_b128 v[236:239], v126 offset:3200
	s_nop 0
	v_add_f32_dpp v14, v14, v14 row_mirror row_mask:0xf bank_mask:0xf bound_ctrl:1
	v_pk_fma_f32 v[8:9], v[14:15], v[192:193], v[252:253] op_sel_hi:[0,1,1]
	v_pk_fma_f32 v[10:11], v[14:15], v[194:195], v[254:255] op_sel_hi:[0,1,1]
	s_waitcnt lgkmcnt(5)
	v_pk_mul_f32 v[250:251], v[8:9], v[206:207]
	v_pk_mul_f32 v[252:253], v[136:137], v[218:219] op_sel:[1,0] op_sel_hi:[1,1]
	v_pk_fma_f32 v[250:251], v[10:11], v[208:209], v[250:251]
	v_pk_mul_f32 v[254:255], v[136:137], v[220:221] op_sel:[1,0] op_sel_hi:[1,1]
	v_add_f32_e32 v14, v250, v251
	v_pk_fma_f32 v[252:253], v[8:9], v[210:211], v[252:253]
	v_pk_fma_f32 v[254:255], v[10:11], v[212:213], v[254:255]
	v_add_f32_dpp v14, v14, v14 quad_perm:[1,0,3,2] row_mask:0xf bank_mask:0xf bound_ctrl:1
	v_pk_mul_f32 v[12:13], v[8:9], v[200:201]
	s_nop 0
	v_add_f32_dpp v14, v14, v14 quad_perm:[2,3,0,1] row_mask:0xf bank_mask:0xf bound_ctrl:1
	v_pk_fma_f32 v[12:13], v[10:11], v[202:203], v[12:13]
	s_nop 0
	v_add_f32_dpp v14, v14, v14 row_half_mirror row_mask:0xf bank_mask:0xf bound_ctrl:1
	v_add_f32_e32 v18, v12, v13
	s_nop 0
	v_add_f32_dpp v14, v14, v14 row_mirror row_mask:0xf bank_mask:0xf bound_ctrl:1
	v_pk_fma_f32 v[8:9], v[14:15], v[214:215], v[252:253] op_sel_hi:[0,1,1]
	v_pk_fma_f32 v[10:11], v[14:15], v[216:217], v[254:255] op_sel_hi:[0,1,1]
	ds_read_b128 v[184:187], v126 offset:4032
	ds_read_b128 v[196:199], v126 offset:4800
	ds_read_b128 v[188:191], v126 offset:4288
	ds_read_b128 v[200:203], v126 offset:5056
	ds_read_b128 v[192:195], v126 offset:4544
	s_waitcnt lgkmcnt(5)
	v_pk_mul_f32 v[250:251], v[8:9], v[228:229]
	v_pk_mul_f32 v[252:253], v[138:139], v[240:241] op_sel_hi:[0,1]
	v_pk_fma_f32 v[250:251], v[10:11], v[230:231], v[250:251]
	v_pk_mul_f32 v[254:255], v[138:139], v[242:243] op_sel_hi:[0,1]
	v_add_f32_e32 v14, v250, v251
	v_pk_fma_f32 v[252:253], v[8:9], v[232:233], v[252:253]
	v_pk_fma_f32 v[254:255], v[10:11], v[234:235], v[254:255]
	v_add_f32_dpp v14, v14, v14 quad_perm:[1,0,3,2] row_mask:0xf bank_mask:0xf bound_ctrl:1
	v_pk_mul_f32 v[12:13], v[8:9], v[222:223]
	s_nop 0
	v_add_f32_dpp v14, v14, v14 quad_perm:[2,3,0,1] row_mask:0xf bank_mask:0xf bound_ctrl:1
	v_pk_fma_f32 v[12:13], v[10:11], v[224:225], v[12:13]
	s_nop 0
	v_add_f32_dpp v14, v14, v14 row_half_mirror row_mask:0xf bank_mask:0xf bound_ctrl:1
	v_add_f32_e32 v19, v12, v13
	s_nop 0
	v_add_f32_dpp v14, v14, v14 row_mirror row_mask:0xf bank_mask:0xf bound_ctrl:1
	v_pk_fma_f32 v[8:9], v[14:15], v[236:237], v[252:253] op_sel_hi:[0,1,1]
	v_pk_fma_f32 v[10:11], v[14:15], v[238:239], v[254:255] op_sel_hi:[0,1,1]
	ds_read_b128 v[140:143], v127 offset:16
	ds_read_b128 v[206:209], v126 offset:5376
	ds_read_b128 v[218:221], v126 offset:6144
	ds_read_b128 v[210:213], v126 offset:5632
	ds_read_b128 v[222:225], v126 offset:6400
	ds_read_b128 v[214:217], v126 offset:5888
	s_waitcnt lgkmcnt(6)
	v_pk_mul_f32 v[250:251], v[8:9], v[184:185]
	v_pk_mul_f32 v[252:253], v[138:139], v[196:197] op_sel:[1,0] op_sel_hi:[1,1]
	v_pk_fma_f32 v[250:251], v[10:11], v[186:187], v[250:251]
	v_pk_mul_f32 v[254:255], v[138:139], v[198:199] op_sel:[1,0] op_sel_hi:[1,1]
	v_add_f32_e32 v14, v250, v251
	v_pk_fma_f32 v[252:253], v[8:9], v[188:189], v[252:253]
	v_pk_fma_f32 v[254:255], v[10:11], v[190:191], v[254:255]
	v_add_f32_dpp v14, v14, v14 quad_perm:[1,0,3,2] row_mask:0xf bank_mask:0xf bound_ctrl:1
	v_pk_mul_f32 v[12:13], v[8:9], v[244:245]
	s_nop 0
	v_add_f32_dpp v14, v14, v14 quad_perm:[2,3,0,1] row_mask:0xf bank_mask:0xf bound_ctrl:1
	v_pk_fma_f32 v[12:13], v[10:11], v[246:247], v[12:13]
	s_nop 0
	v_add_f32_dpp v14, v14, v14 row_half_mirror row_mask:0xf bank_mask:0xf bound_ctrl:1
	v_add_f32_e32 v20, v12, v13
	s_nop 0
	v_add_f32_dpp v14, v14, v14 row_mirror row_mask:0xf bank_mask:0xf bound_ctrl:1
	v_pk_fma_f32 v[8:9], v[14:15], v[192:193], v[252:253] op_sel_hi:[0,1,1]
	v_pk_fma_f32 v[10:11], v[14:15], v[194:195], v[254:255] op_sel_hi:[0,1,1]
	ds_read_b128 v[228:231], v126 offset:6720
	ds_read_b128 v[240:243], v126 offset:7488
	ds_read_b128 v[232:235], v126 offset:6976
	ds_read_b128 v[244:247], v126 offset:7744
	ds_read_b128 v[236:239], v126 offset:7232
	s_waitcnt lgkmcnt(5)
	v_pk_mul_f32 v[250:251], v[8:9], v[206:207]
	v_pk_mul_f32 v[252:253], v[140:141], v[218:219] op_sel_hi:[0,1]
	v_pk_fma_f32 v[250:251], v[10:11], v[208:209], v[250:251]
	v_pk_mul_f32 v[254:255], v[140:141], v[220:221] op_sel_hi:[0,1]
	v_add_f32_e32 v14, v250, v251
	v_pk_fma_f32 v[252:253], v[8:9], v[210:211], v[252:253]
	v_pk_fma_f32 v[254:255], v[10:11], v[212:213], v[254:255]
	v_add_f32_dpp v14, v14, v14 quad_perm:[1,0,3,2] row_mask:0xf bank_mask:0xf bound_ctrl:1
	v_pk_mul_f32 v[12:13], v[8:9], v[200:201]
	s_nop 0
	v_add_f32_dpp v14, v14, v14 quad_perm:[2,3,0,1] row_mask:0xf bank_mask:0xf bound_ctrl:1
	v_pk_fma_f32 v[12:13], v[10:11], v[202:203], v[12:13]
	s_nop 0
	v_add_f32_dpp v14, v14, v14 row_half_mirror row_mask:0xf bank_mask:0xf bound_ctrl:1
	v_add_f32_e32 v21, v12, v13
	s_nop 0
	v_add_f32_dpp v14, v14, v14 row_mirror row_mask:0xf bank_mask:0xf bound_ctrl:1
	v_pk_fma_f32 v[8:9], v[14:15], v[214:215], v[252:253] op_sel_hi:[0,1,1]
	v_pk_fma_f32 v[10:11], v[14:15], v[216:217], v[254:255] op_sel_hi:[0,1,1]
	ds_read_b128 v[184:187], v126 offset:8064
	ds_read_b128 v[196:199], v126 offset:8832
	ds_read_b128 v[188:191], v126 offset:8320
	ds_read_b128 v[200:203], v126 offset:9088
	ds_read_b128 v[192:195], v126 offset:8576
	s_waitcnt lgkmcnt(5)
	v_pk_mul_f32 v[250:251], v[8:9], v[228:229]
	v_pk_mul_f32 v[252:253], v[140:141], v[240:241] op_sel:[1,0] op_sel_hi:[1,1]
	v_pk_fma_f32 v[250:251], v[10:11], v[230:231], v[250:251]
	v_pk_mul_f32 v[254:255], v[140:141], v[242:243] op_sel:[1,0] op_sel_hi:[1,1]
	v_add_f32_e32 v14, v250, v251
	v_pk_fma_f32 v[252:253], v[8:9], v[232:233], v[252:253]
	v_pk_fma_f32 v[254:255], v[10:11], v[234:235], v[254:255]
	v_add_f32_dpp v14, v14, v14 quad_perm:[1,0,3,2] row_mask:0xf bank_mask:0xf bound_ctrl:1
	v_pk_mul_f32 v[12:13], v[8:9], v[222:223]
	s_nop 0
	v_add_f32_dpp v14, v14, v14 quad_perm:[2,3,0,1] row_mask:0xf bank_mask:0xf bound_ctrl:1
	v_pk_fma_f32 v[12:13], v[10:11], v[224:225], v[12:13]
	s_nop 0
	v_add_f32_dpp v14, v14, v14 row_half_mirror row_mask:0xf bank_mask:0xf bound_ctrl:1
	v_add_f32_e32 v22, v12, v13
	s_nop 0
	v_add_f32_dpp v14, v14, v14 row_mirror row_mask:0xf bank_mask:0xf bound_ctrl:1
	v_pk_fma_f32 v[8:9], v[14:15], v[236:237], v[252:253] op_sel_hi:[0,1,1]
	v_pk_fma_f32 v[10:11], v[14:15], v[238:239], v[254:255] op_sel_hi:[0,1,1]
	ds_read_b128 v[206:209], v126 offset:9408
	ds_read_b128 v[218:221], v126 offset:10176
	ds_read_b128 v[210:213], v126 offset:9664
	ds_read_b128 v[222:225], v126 offset:10432
	ds_read_b128 v[214:217], v126 offset:9920
	s_waitcnt lgkmcnt(5)
	v_pk_mul_f32 v[250:251], v[8:9], v[184:185]
	v_pk_mul_f32 v[252:253], v[142:143], v[196:197] op_sel_hi:[0,1]
	v_pk_fma_f32 v[250:251], v[10:11], v[186:187], v[250:251]
	v_pk_mul_f32 v[254:255], v[142:143], v[198:199] op_sel_hi:[0,1]
	v_add_f32_e32 v14, v250, v251
	v_pk_fma_f32 v[252:253], v[8:9], v[188:189], v[252:253]
	v_pk_fma_f32 v[254:255], v[10:11], v[190:191], v[254:255]
	v_add_f32_dpp v14, v14, v14 quad_perm:[1,0,3,2] row_mask:0xf bank_mask:0xf bound_ctrl:1
	v_pk_mul_f32 v[12:13], v[8:9], v[244:245]
	s_nop 0
	v_add_f32_dpp v14, v14, v14 quad_perm:[2,3,0,1] row_mask:0xf bank_mask:0xf bound_ctrl:1
	v_pk_fma_f32 v[12:13], v[10:11], v[246:247], v[12:13]
	s_nop 0
	v_add_f32_dpp v14, v14, v14 row_half_mirror row_mask:0xf bank_mask:0xf bound_ctrl:1
	v_add_f32_e32 v23, v12, v13
	s_nop 0
	v_add_f32_dpp v14, v14, v14 row_mirror row_mask:0xf bank_mask:0xf bound_ctrl:1
	v_pk_fma_f32 v[8:9], v[14:15], v[192:193], v[252:253] op_sel_hi:[0,1,1]
	v_pk_fma_f32 v[10:11], v[14:15], v[194:195], v[254:255] op_sel_hi:[0,1,1]
	ds_read_b128 v[136:139], v127 offset:32
	ds_read_b128 v[228:231], v126 offset:10752
	ds_read_b128 v[240:243], v126 offset:11520
	ds_read_b128 v[232:235], v126 offset:11008
	ds_read_b128 v[244:247], v126 offset:11776
	ds_read_b128 v[236:239], v126 offset:11264
	s_waitcnt lgkmcnt(6)
	v_pk_mul_f32 v[250:251], v[8:9], v[206:207]
	v_pk_mul_f32 v[252:253], v[142:143], v[218:219] op_sel:[1,0] op_sel_hi:[1,1]
	v_pk_fma_f32 v[250:251], v[10:11], v[208:209], v[250:251]
	v_pk_mul_f32 v[254:255], v[142:143], v[220:221] op_sel:[1,0] op_sel_hi:[1,1]
	v_add_f32_e32 v14, v250, v251
	v_pk_fma_f32 v[252:253], v[8:9], v[210:211], v[252:253]
	v_pk_fma_f32 v[254:255], v[10:11], v[212:213], v[254:255]
	v_add_f32_dpp v14, v14, v14 quad_perm:[1,0,3,2] row_mask:0xf bank_mask:0xf bound_ctrl:1
	v_pk_mul_f32 v[12:13], v[8:9], v[200:201]
	s_nop 0
	v_add_f32_dpp v14, v14, v14 quad_perm:[2,3,0,1] row_mask:0xf bank_mask:0xf bound_ctrl:1
	v_pk_fma_f32 v[12:13], v[10:11], v[202:203], v[12:13]
	s_nop 0
	v_add_f32_dpp v14, v14, v14 row_half_mirror row_mask:0xf bank_mask:0xf bound_ctrl:1
	v_add_f32_e32 v24, v12, v13
	s_nop 0
	v_add_f32_dpp v14, v14, v14 row_mirror row_mask:0xf bank_mask:0xf bound_ctrl:1
	v_pk_fma_f32 v[8:9], v[14:15], v[214:215], v[252:253] op_sel_hi:[0,1,1]
	v_pk_fma_f32 v[10:11], v[14:15], v[216:217], v[254:255] op_sel_hi:[0,1,1]
	ds_read_b128 v[184:187], v126 offset:12096
	ds_read_b128 v[196:199], v126 offset:12864
	ds_read_b128 v[188:191], v126 offset:12352
	ds_read_b128 v[200:203], v126 offset:13120
	ds_read_b128 v[192:195], v126 offset:12608
	s_waitcnt lgkmcnt(5)
	v_pk_mul_f32 v[250:251], v[8:9], v[228:229]
	v_pk_mul_f32 v[252:253], v[136:137], v[240:241] op_sel_hi:[0,1]
	v_pk_fma_f32 v[250:251], v[10:11], v[230:231], v[250:251]
	v_pk_mul_f32 v[254:255], v[136:137], v[242:243] op_sel_hi:[0,1]
	v_add_f32_e32 v14, v250, v251
	v_pk_fma_f32 v[252:253], v[8:9], v[232:233], v[252:253]
	v_pk_fma_f32 v[254:255], v[10:11], v[234:235], v[254:255]
	v_add_f32_dpp v14, v14, v14 quad_perm:[1,0,3,2] row_mask:0xf bank_mask:0xf bound_ctrl:1
	v_pk_mul_f32 v[12:13], v[8:9], v[222:223]
	s_nop 0
	v_add_f32_dpp v14, v14, v14 quad_perm:[2,3,0,1] row_mask:0xf bank_mask:0xf bound_ctrl:1
	v_pk_fma_f32 v[12:13], v[10:11], v[224:225], v[12:13]
	s_nop 0
	v_add_f32_dpp v14, v14, v14 row_half_mirror row_mask:0xf bank_mask:0xf bound_ctrl:1
	v_add_f32_e32 v25, v12, v13
	s_nop 0
	v_add_f32_dpp v14, v14, v14 row_mirror row_mask:0xf bank_mask:0xf bound_ctrl:1
	v_pk_fma_f32 v[8:9], v[14:15], v[236:237], v[252:253] op_sel_hi:[0,1,1]
	v_pk_fma_f32 v[10:11], v[14:15], v[238:239], v[254:255] op_sel_hi:[0,1,1]
	ds_read_b128 v[206:209], v126 offset:13440
	ds_read_b128 v[218:221], v126 offset:14208
	ds_read_b128 v[210:213], v126 offset:13696
	ds_read_b128 v[222:225], v126 offset:14464
	ds_read_b128 v[214:217], v126 offset:13952
	s_waitcnt vmcnt(0)
	s_xor_b32 s0, s11, 1
	v_lshl_add_u32 v170, s0, 10, v130
	s_mulk_i32 s0, 0x5400
	v_add_u32_e32 v82, s0, v79
	v_lshlrev_b32_e32 v34, 16, v74
	v_and_b32_e32 v35, 0xffff0000, v74
	v_lshlrev_b32_e32 v36, 16, v75
	v_and_b32_e32 v37, 0xffff0000, v75
	v_lshl_add_u32 v83, v50, 2, v82
	v_pk_mul_f32 v[38:39], v[0:1], v[34:35]
	v_pk_mul_f32 v[40:41], v[2:3], v[36:37]
	v_lshlrev_b32_e32 v120, 16, v72
	v_pk_mul_f32 v[42:43], v[78:79], v[38:39] op_sel_hi:[0,1] neg_lo:[1,0] neg_hi:[1,0]
	v_pk_mul_f32 v[44:45], v[78:79], v[40:41] op_sel_hi:[0,1] neg_lo:[1,0] neg_hi:[1,0]
	v_and_b32_e32 v121, 0xffff0000, v72
	v_lshlrev_b32_e32 v122, 16, v73
	v_and_b32_e32 v123, 0xffff0000, v73
	ds_write_b128 v83, v[42:45]
	v_lshlrev_b32_e32 v38, 16, v76
	v_and_b32_e32 v39, 0xffff0000, v76
	v_lshlrev_b32_e32 v40, 16, v77
	v_and_b32_e32 v41, 0xffff0000, v77
	v_pk_add_f32 v[38:39], v[38:39], 1.0 op_sel_hi:[1,0] neg_lo:[1,0] neg_hi:[1,0]
	v_pk_add_f32 v[40:41], v[40:41], 1.0 op_sel_hi:[1,0] neg_lo:[1,0] neg_hi:[1,0]
	v_lshl_add_u32 v85, v48, 2, v82
	ds_write_b128 v83, v[38:41] offset:256
	v_pk_mul_f32 v[38:39], v[42:43], v[120:121] neg_lo:[1,0] neg_hi:[1,0]
	v_pk_mul_f32 v[40:41], v[44:45], v[122:123] neg_lo:[1,0] neg_hi:[1,0]
	v_pk_add_f32 v[120:121], v[120:121], -1.0 op_sel_hi:[1,0]
	v_pk_add_f32 v[122:123], v[122:123], -1.0 op_sel_hi:[1,0]
	ds_write_b128 v83, v[38:41] offset:512
	v_pk_fma_f32 v[120:121], v[4:5], v[120:121], 1.0 op_sel_hi:[1,1,0]
	v_pk_fma_f32 v[122:123], v[6:7], v[122:123], 1.0 op_sel_hi:[1,1,0]
	v_lshlrev_b32_e32 v42, 16, v62
	v_and_b32_e32 v43, 0xffff0000, v62
	v_pk_mul_f32 v[120:121], v[120:121], v[34:35]
	v_pk_mul_f32 v[122:123], v[122:123], v[36:37]
	v_lshlrev_b32_e32 v44, 16, v63
	v_and_b32_e32 v45, 0xffff0000, v63
	v_lshlrev_b32_e32 v84, 16, v102
	ds_write_b128 v83, v[120:123] offset:768
	ds_write_b128 v83, v[42:45] offset:1024
	ds_write_b32 v85, v84 offset:1280
	ds_write_b32 v170, v84
	s_cmpk_eq_i32 s6, 0x20e0
	s_cbranch_scc1 .Lscan_pf_skip
	v_add_u32_e32 v131, v132, v131
	s_cmp_eq_u32 s10, 14
	s_cbranch_scc0 .Lscan_pf_nox
	v_mov_b32_e32 v131, v133

.Lscan_pf_skip:
	s_waitcnt lgkmcnt(12)
	v_pk_mul_f32 v[250:251], v[8:9], v[184:185]
	v_pk_mul_f32 v[252:253], v[136:137], v[196:197] op_sel:[1,0] op_sel_hi:[1,1]
	v_pk_fma_f32 v[250:251], v[10:11], v[186:187], v[250:251]
	v_pk_mul_f32 v[254:255], v[136:137], v[198:199] op_sel:[1,0] op_sel_hi:[1,1]
	v_add_f32_e32 v14, v250, v251
	v_pk_fma_f32 v[252:253], v[8:9], v[188:189], v[252:253]
	v_pk_fma_f32 v[254:255], v[10:11], v[190:191], v[254:255]
	v_add_f32_dpp v14, v14, v14 quad_perm:[1,0,3,2] row_mask:0xf bank_mask:0xf bound_ctrl:1
	v_pk_mul_f32 v[12:13], v[8:9], v[244:245]
	s_nop 0
	v_add_f32_dpp v14, v14, v14 quad_perm:[2,3,0,1] row_mask:0xf bank_mask:0xf bound_ctrl:1
	v_pk_fma_f32 v[12:13], v[10:11], v[246:247], v[12:13]
	s_nop 0
	v_add_f32_dpp v14, v14, v14 row_half_mirror row_mask:0xf bank_mask:0xf bound_ctrl:1
	v_add_f32_e32 v26, v12, v13
	s_nop 0
	v_add_f32_dpp v14, v14, v14 row_mirror row_mask:0xf bank_mask:0xf bound_ctrl:1
	v_pk_fma_f32 v[8:9], v[14:15], v[192:193], v[252:253] op_sel_hi:[0,1,1]
	v_pk_fma_f32 v[10:11], v[14:15], v[194:195], v[254:255] op_sel_hi:[0,1,1]
	ds_read_b128 v[228:231], v126 offset:14784
	ds_read_b128 v[240:243], v126 offset:15552
	ds_read_b128 v[232:235], v126 offset:15040
	ds_read_b128 v[244:247], v126 offset:15808
	ds_read_b128 v[236:239], v126 offset:15296
	s_waitcnt lgkmcnt(12)
	v_pk_mul_f32 v[250:251], v[8:9], v[206:207]
	v_pk_mul_f32 v[252:253], v[138:139], v[218:219] op_sel_hi:[0,1]
	v_pk_fma_f32 v[250:251], v[10:11], v[208:209], v[250:251]
	v_pk_mul_f32 v[254:255], v[138:139], v[220:221] op_sel_hi:[0,1]
	v_add_f32_e32 v14, v250, v251
	v_pk_fma_f32 v[252:253], v[8:9], v[210:211], v[252:253]
	v_pk_fma_f32 v[254:255], v[10:11], v[212:213], v[254:255]
	v_add_f32_dpp v14, v14, v14 quad_perm:[1,0,3,2] row_mask:0xf bank_mask:0xf bound_ctrl:1
	v_pk_mul_f32 v[12:13], v[8:9], v[200:201]
	s_nop 0
	v_add_f32_dpp v14, v14, v14 quad_perm:[2,3,0,1] row_mask:0xf bank_mask:0xf bound_ctrl:1
	v_pk_fma_f32 v[12:13], v[10:11], v[202:203], v[12:13]
	s_nop 0
	v_add_f32_dpp v14, v14, v14 row_half_mirror row_mask:0xf bank_mask:0xf bound_ctrl:1
	v_add_f32_e32 v27, v12, v13
	s_nop 0
	v_add_f32_dpp v14, v14, v14 row_mirror row_mask:0xf bank_mask:0xf bound_ctrl:1
	v_pk_fma_f32 v[8:9], v[14:15], v[214:215], v[252:253] op_sel_hi:[0,1,1]
	v_pk_fma_f32 v[10:11], v[14:15], v[216:217], v[254:255] op_sel_hi:[0,1,1]
	ds_read_b128 v[140:143], v127 offset:48
	ds_read_b128 v[184:187], v126 offset:16128
	ds_read_b128 v[196:199], v126 offset:16896
	ds_read_b128 v[188:191], v126 offset:16384
	ds_read_b128 v[200:203], v126 offset:17152
	ds_read_b128 v[192:195], v126 offset:16640
	s_waitcnt lgkmcnt(6)
	v_pk_mul_f32 v[250:251], v[8:9], v[228:229]
	v_pk_mul_f32 v[252:253], v[138:139], v[240:241] op_sel:[1,0] op_sel_hi:[1,1]
	v_pk_fma_f32 v[250:251], v[10:11], v[230:231], v[250:251]
	v_pk_mul_f32 v[254:255], v[138:139], v[242:243] op_sel:[1,0] op_sel_hi:[1,1]
	v_add_f32_e32 v14, v250, v251
	v_pk_fma_f32 v[252:253], v[8:9], v[232:233], v[252:253]
	v_pk_fma_f32 v[254:255], v[10:11], v[234:235], v[254:255]
	v_add_f32_dpp v14, v14, v14 quad_perm:[1,0,3,2] row_mask:0xf bank_mask:0xf bound_ctrl:1
	v_pk_mul_f32 v[12:13], v[8:9], v[222:223]
	s_nop 0
	v_add_f32_dpp v14, v14, v14 quad_perm:[2,3,0,1] row_mask:0xf bank_mask:0xf bound_ctrl:1
	v_pk_fma_f32 v[12:13], v[10:11], v[224:225], v[12:13]
	s_nop 0
	v_add_f32_dpp v14, v14, v14 row_half_mirror row_mask:0xf bank_mask:0xf bound_ctrl:1
	v_add_f32_e32 v28, v12, v13
	s_nop 0
	v_add_f32_dpp v14, v14, v14 row_mirror row_mask:0xf bank_mask:0xf bound_ctrl:1
	v_pk_fma_f32 v[8:9], v[14:15], v[236:237], v[252:253] op_sel_hi:[0,1,1]
	v_pk_fma_f32 v[10:11], v[14:15], v[238:239], v[254:255] op_sel_hi:[0,1,1]
	ds_read_b128 v[206:209], v126 offset:17472
	ds_read_b128 v[218:221], v126 offset:18240
	ds_read_b128 v[210:213], v126 offset:17728
	ds_read_b128 v[222:225], v126 offset:18496
	ds_read_b128 v[214:217], v126 offset:17984
	s_waitcnt lgkmcnt(5)
	v_pk_mul_f32 v[250:251], v[8:9], v[184:185]
	v_pk_mul_f32 v[252:253], v[140:141], v[196:197] op_sel_hi:[0,1]
	v_pk_fma_f32 v[250:251], v[10:11], v[186:187], v[250:251]
	v_pk_mul_f32 v[254:255], v[140:141], v[198:199] op_sel_hi:[0,1]
	v_add_f32_e32 v14, v250, v251
	v_pk_fma_f32 v[252:253], v[8:9], v[188:189], v[252:253]
	v_pk_fma_f32 v[254:255], v[10:11], v[190:191], v[254:255]
	v_add_f32_dpp v14, v14, v14 quad_perm:[1,0,3,2] row_mask:0xf bank_mask:0xf bound_ctrl:1
	v_pk_mul_f32 v[12:13], v[8:9], v[244:245]
	s_nop 0
	v_add_f32_dpp v14, v14, v14 quad_perm:[2,3,0,1] row_mask:0xf bank_mask:0xf bound_ctrl:1
	v_pk_fma_f32 v[12:13], v[10:11], v[246:247], v[12:13]
	s_nop 0
	v_add_f32_dpp v14, v14, v14 row_half_mirror row_mask:0xf bank_mask:0xf bound_ctrl:1
	v_add_f32_e32 v29, v12, v13
	s_nop 0
	v_add_f32_dpp v14, v14, v14 row_mirror row_mask:0xf bank_mask:0xf bound_ctrl:1
	v_pk_fma_f32 v[8:9], v[14:15], v[192:193], v[252:253] op_sel_hi:[0,1,1]
	v_pk_fma_f32 v[10:11], v[14:15], v[194:195], v[254:255] op_sel_hi:[0,1,1]
	ds_read_b128 v[228:231], v126 offset:18816
	ds_read_b128 v[240:243], v126 offset:19584
	ds_read_b128 v[232:235], v126 offset:19072
	ds_read_b128 v[244:247], v126 offset:19840
	ds_read_b128 v[236:239], v126 offset:19328
	s_waitcnt lgkmcnt(5)
	v_pk_mul_f32 v[250:251], v[8:9], v[206:207]
	v_pk_mul_f32 v[252:253], v[140:141], v[218:219] op_sel:[1,0] op_sel_hi:[1,1]
	v_pk_fma_f32 v[250:251], v[10:11], v[208:209], v[250:251]
	v_pk_mul_f32 v[254:255], v[140:141], v[220:221] op_sel:[1,0] op_sel_hi:[1,1]
	v_add_f32_e32 v14, v250, v251
	v_pk_fma_f32 v[252:253], v[8:9], v[210:211], v[252:253]
	v_pk_fma_f32 v[254:255], v[10:11], v[212:213], v[254:255]
	v_add_f32_dpp v14, v14, v14 quad_perm:[1,0,3,2] row_mask:0xf bank_mask:0xf bound_ctrl:1
	v_pk_mul_f32 v[12:13], v[8:9], v[200:201]
	s_nop 0
	v_add_f32_dpp v14, v14, v14 quad_perm:[2,3,0,1] row_mask:0xf bank_mask:0xf bound_ctrl:1
	v_pk_fma_f32 v[12:13], v[10:11], v[202:203], v[12:13]
	s_nop 0
	v_add_f32_dpp v14, v14, v14 row_half_mirror row_mask:0xf bank_mask:0xf bound_ctrl:1
	v_add_f32_e32 v30, v12, v13
	s_nop 0
	v_add_f32_dpp v14, v14, v14 row_mirror row_mask:0xf bank_mask:0xf bound_ctrl:1
	v_pk_fma_f32 v[8:9], v[14:15], v[214:215], v[252:253] op_sel_hi:[0,1,1]
	v_pk_fma_f32 v[10:11], v[14:15], v[216:217], v[254:255] op_sel_hi:[0,1,1]
	ds_read_b128 v[184:187], v126 offset:20160
	ds_read_b128 v[196:199], v126 offset:20928
	ds_read_b128 v[188:191], v126 offset:20416
	ds_read_b128 v[200:203], v126 offset:21184
	ds_read_b128 v[192:195], v126 offset:20672
	s_waitcnt lgkmcnt(5)
	v_pk_mul_f32 v[250:251], v[8:9], v[228:229]
	v_pk_mul_f32 v[252:253], v[142:143], v[240:241] op_sel_hi:[0,1]
	v_pk_fma_f32 v[250:251], v[10:11], v[230:231], v[250:251]
	v_pk_mul_f32 v[254:255], v[142:143], v[242:243] op_sel_hi:[0,1]
	v_add_f32_e32 v14, v250, v251
	v_pk_fma_f32 v[252:253], v[8:9], v[232:233], v[252:253]
	v_pk_fma_f32 v[254:255], v[10:11], v[234:235], v[254:255]
	v_add_f32_dpp v14, v14, v14 quad_perm:[1,0,3,2] row_mask:0xf bank_mask:0xf bound_ctrl:1
	v_pk_mul_f32 v[12:13], v[8:9], v[222:223]
	s_nop 0
	v_add_f32_dpp v14, v14, v14 quad_perm:[2,3,0,1] row_mask:0xf bank_mask:0xf bound_ctrl:1
	v_pk_fma_f32 v[12:13], v[10:11], v[224:225], v[12:13]
	s_nop 0
	v_add_f32_dpp v14, v14, v14 row_half_mirror row_mask:0xf bank_mask:0xf bound_ctrl:1
	v_add_f32_e32 v31, v12, v13
	s_nop 0
	v_add_f32_dpp v14, v14, v14 row_mirror row_mask:0xf bank_mask:0xf bound_ctrl:1
	v_pk_fma_f32 v[8:9], v[14:15], v[236:237], v[252:253] op_sel_hi:[0,1,1]
	v_pk_fma_f32 v[10:11], v[14:15], v[238:239], v[254:255] op_sel_hi:[0,1,1]
	s_waitcnt lgkmcnt(0)
	v_pk_mul_f32 v[250:251], v[8:9], v[184:185]
	v_pk_mul_f32 v[252:253], v[142:143], v[196:197] op_sel:[1,0] op_sel_hi:[1,1]
	v_pk_fma_f32 v[250:251], v[10:11], v[186:187], v[250:251]
	v_pk_mul_f32 v[254:255], v[142:143], v[198:199] op_sel:[1,0] op_sel_hi:[1,1]
	v_add_f32_e32 v14, v250, v251
	v_pk_fma_f32 v[252:253], v[8:9], v[188:189], v[252:253]
	v_pk_fma_f32 v[254:255], v[10:11], v[190:191], v[254:255]
	v_add_f32_dpp v14, v14, v14 quad_perm:[1,0,3,2] row_mask:0xf bank_mask:0xf bound_ctrl:1
	v_pk_mul_f32 v[12:13], v[8:9], v[244:245]
	s_nop 0
	v_add_f32_dpp v14, v14, v14 quad_perm:[2,3,0,1] row_mask:0xf bank_mask:0xf bound_ctrl:1
	v_pk_fma_f32 v[12:13], v[10:11], v[246:247], v[12:13]
	s_nop 0
	v_add_f32_dpp v14, v14, v14 row_half_mirror row_mask:0xf bank_mask:0xf bound_ctrl:1
	v_add_f32_e32 v32, v12, v13
	s_nop 0
	v_add_f32_dpp v14, v14, v14 row_mirror row_mask:0xf bank_mask:0xf bound_ctrl:1
	v_pk_fma_f32 v[8:9], v[14:15], v[192:193], v[252:253] op_sel_hi:[0,1,1]
	v_pk_fma_f32 v[10:11], v[14:15], v[194:195], v[254:255] op_sel_hi:[0,1,1]
	v_pk_mul_f32 v[12:13], v[8:9], v[200:201]
	v_add_f32_dpp v34, v18, v18 row_mirror row_mask:0xf bank_mask:0x3 bound_ctrl:1
	v_pk_fma_f32 v[12:13], v[10:11], v[202:203], v[12:13]
	v_add_f32_dpp v35, v19, v19 row_mirror row_mask:0xf bank_mask:0x3 bound_ctrl:1
	v_add_f32_dpp v36, v20, v20 row_mirror row_mask:0xf bank_mask:0x3 bound_ctrl:1
	v_add_f32_e32 v33, v12, v13
	v_add_f32_dpp v37, v21, v21 row_mirror row_mask:0xf bank_mask:0x3 bound_ctrl:1
	v_add_f32_dpp v38, v22, v22 row_mirror row_mask:0xf bank_mask:0x3 bound_ctrl:1
	v_add_f32_dpp v39, v23, v23 row_mirror row_mask:0xf bank_mask:0x3 bound_ctrl:1
	v_add_f32_dpp v40, v24, v24 row_mirror row_mask:0xf bank_mask:0x3 bound_ctrl:1
	v_add_f32_dpp v41, v25, v25 row_mirror row_mask:0xf bank_mask:0x3 bound_ctrl:1
	v_add_f32_dpp v34, v26, v26 row_mirror row_mask:0xf bank_mask:0xc bound_ctrl:1
	v_add_f32_dpp v35, v27, v27 row_mirror row_mask:0xf bank_mask:0xc bound_ctrl:1
	v_add_f32_dpp v36, v28, v28 row_mirror row_mask:0xf bank_mask:0xc bound_ctrl:1
	v_add_f32_dpp v37, v29, v29 row_mirror row_mask:0xf bank_mask:0xc bound_ctrl:1
	v_add_f32_dpp v38, v30, v30 row_mirror row_mask:0xf bank_mask:0xc bound_ctrl:1
	v_add_f32_dpp v39, v31, v31 row_mirror row_mask:0xf bank_mask:0xc bound_ctrl:1
	v_add_f32_dpp v40, v32, v32 row_mirror row_mask:0xf bank_mask:0xc bound_ctrl:1
	v_add_f32_dpp v41, v33, v33 row_mirror row_mask:0xf bank_mask:0xc bound_ctrl:1
	v_add_f32_dpp v42, v34, v34 row_half_mirror row_mask:0xf bank_mask:0x5 bound_ctrl:1
	v_add_f32_dpp v43, v35, v35 row_half_mirror row_mask:0xf bank_mask:0x5 bound_ctrl:1
	v_add_f32_dpp v44, v36, v36 row_half_mirror row_mask:0xf bank_mask:0x5 bound_ctrl:1
	v_add_f32_dpp v45, v37, v37 row_half_mirror row_mask:0xf bank_mask:0x5 bound_ctrl:1
	v_add_f32_dpp v42, v38, v38 row_half_mirror row_mask:0xf bank_mask:0xa bound_ctrl:1
	v_add_f32_dpp v43, v39, v39 row_half_mirror row_mask:0xf bank_mask:0xa bound_ctrl:1
	v_add_f32_dpp v44, v40, v40 row_half_mirror row_mask:0xf bank_mask:0xa bound_ctrl:1
	v_add_f32_dpp v45, v41, v41 row_half_mirror row_mask:0xf bank_mask:0xa bound_ctrl:1
	v_cndmask_b32_e64 v80, v44, v42, s[42:43]
	v_cndmask_b32_e64 v121, v42, v44, s[42:43]
	v_cndmask_b32_e64 v82, v45, v43, s[42:43]
	v_cndmask_b32_e64 v122, v43, v45, s[42:43]
	s_nop 0
	s_nop 0
	v_add_f32_dpp v13, v121, v80 quad_perm:[2,3,0,1] row_mask:0xf bank_mask:0xf bound_ctrl:1
	v_add_f32_dpp v14, v122, v82 quad_perm:[2,3,0,1] row_mask:0xf bank_mask:0xf bound_ctrl:1
	v_cndmask_b32_e64 v12, v13, v14, s[44:45]
	v_cndmask_b32_e64 v13, v14, v13, s[44:45]
	v_lshl_add_u32 v16, v100, 11, v99
	v_add_u32_e32 v100, v132, v100
	v_add_f32_dpp v13, v12, v13 quad_perm:[1,0,3,2] row_mask:0xf bank_mask:0xf bound_ctrl:1
	s_cmp_eq_u32 s10, 15
	s_cbranch_scc0 .Lscan_tail_nox
	v_mov_b32_e32 v100, v101
